# grid barrier: all workgroups poll the top-level generation word directly (one hop fewer); sample_outproj loads batched
# speedup vs baseline: 1.0051x; 1.0020x over previous
; __device__ __forceinline__ unsigned xb_ld(unsigned* p)              { return __hip_atomic_load(p, __ATOMIC_RELAXED, __HIP_MEMORY_SCOPE_AGENT); }
; __device__ __forceinline__ unsigned xb_add(unsigned* p, unsigned v) { return __hip_atomic_fetch_add(p, v, __ATOMIC_RELAXED, __HIP_MEMORY_SCOPE_AGENT); }
; #define XB_SPIN(cond, bar) do { unsigned _sp = 0; while (cond) { __builtin_amdgcn_s_sleep(1); \
;     if ((++_sp & 255u) == 0u) { if (xb_ld(&(bar)[XB_TMO])) break; if (_sp > XB_SPIN_CAP) { atomicAdd(&(bar)[XB_TMO], 1u); break; } } } } while (0)
; __device__ __forceinline__ void xcd_barrier(const XcdBarrier& b) {
;     ...
;         const unsigned old = xb_add(&bar[XB_XSUB(b.x)], 1u);
;         const unsigned gen = old / nloc;
;         if (old + 1u == (gen + 1u) * nloc) {
;             __builtin_amdgcn_fence(__ATOMIC_RELEASE, "agent");
;             asm volatile("s_waitcnt vmcnt(0)" ::: "memory");
;             const unsigned og = xb_add(&bar[XB_TOP], 1u);
;             const unsigned tg = og / nx;
;             if (og + 1u == (tg + 1u) * nx) xb_add(&bar[XB_TOPGEN], 1u);
;             else XB_SPIN(xb_ld(&bar[XB_TOPGEN]) == tg, bar);
;             __builtin_amdgcn_fence(__ATOMIC_ACQUIRE, "agent");
;             xb_add(&bar[XB_XGEN(b.x)], 1u);
;             asm volatile("s_waitcnt vmcnt(0)" ::: "memory");
;         } else {
;             XB_SPIN(xb_ld(&bar[XB_XGEN(b.x)]) == gen, bar);
.LBB0_72:
	s_or_b64 exec, exec, s[2:3]
	v_cvt_f32_u32_e32 v4, v2
	s_waitcnt vmcnt(0)
	v_readfirstlane_b32 s2, v3
	v_sub_u32_e32 v3, 0, v2
	v_rcp_iflag_f32_e32 v4, v4
	v_add_u32_e32 v5, s2, v1
	v_mul_f32_e32 v4, 0x4f7ffffe, v4
	v_cvt_u32_f32_e32 v4, v4
	v_mul_lo_u32 v1, v3, v4
	v_mul_hi_u32 v1, v4, v1
	v_add_u32_e32 v1, v4, v1
	v_mul_hi_u32 v1, v5, v1
	v_mul_lo_u32 v3, v1, v2
	v_sub_u32_e32 v3, v5, v3
	v_add_u32_e32 v4, 1, v1
	v_cmp_ge_u32_e32 vcc, v3, v2
	s_nop 1
	v_cndmask_b32_e32 v1, v1, v4, vcc
	v_sub_u32_e32 v4, v3, v2
	v_cndmask_b32_e32 v3, v3, v4, vcc
	v_add_u32_e32 v4, 1, v1
	v_cmp_ge_u32_e32 vcc, v3, v2
	v_add_u32_e32 v3, 1, v5
	s_nop 0
	v_cndmask_b32_e32 v1, v1, v4, vcc
	v_mul_lo_u32 v4, v2, v1
	v_add_u32_e32 v2, v4, v2
	v_cmp_ne_u32_e32 vcc, v3, v2
	s_and_saveexec_b64 s[2:3], vcc
	s_xor_b64 s[2:3], exec, s[2:3]
	s_cbranch_execz .LBB0_86
	v_readlane_b32 s4, v253, 2
	s_waitcnt lgkmcnt(0)
	v_mov_b32_e32 v0, 0
	v_readlane_b32 s5, v253, 3
	s_nop 4
	global_load_dword v2, v0, s[4:5] sc1
	s_waitcnt vmcnt(0)
	v_cmp_eq_u32_e32 vcc, v2, v1
	s_and_saveexec_b64 s[4:5], vcc
	s_cbranch_execz .LBB0_85
	s_mov_b32 s15, 1
	s_mov_b64 s[6:7], 0
	s_branch .LBB0_76

; __device__ __forceinline__ unsigned xb_ld(unsigned* p)              { return __hip_atomic_load(p, __ATOMIC_RELAXED, __HIP_MEMORY_SCOPE_AGENT); }
; #define XB_SPIN(cond, bar) do { unsigned _sp = 0; while (cond) { __builtin_amdgcn_s_sleep(1); \
;     if ((++_sp & 255u) == 0u) { if (xb_ld(&(bar)[XB_TMO])) break; if (_sp > XB_SPIN_CAP) { atomicAdd(&(bar)[XB_TMO], 1u); break; } } } } while (0)
; __device__ __forceinline__ void xcd_barrier(const XcdBarrier& b) {
;     ...
;             XB_SPIN(xb_ld(&bar[XB_XGEN(b.x)]) == gen, bar);
.LBB0_80:
	v_readlane_b32 s10, v253, 2
	v_readlane_b32 s11, v253, 3
	s_add_i32 s15, s15, 1
	s_mov_b64 s[12:13], -1
	s_nop 2
	global_load_dword v2, v0, s[10:11] sc1
	s_waitcnt vmcnt(0)
	v_cmp_ne_u32_e32 vcc, v2, v1
	s_orn2_b64 s[10:11], vcc, exec
	s_branch .LBB0_75

; __device__ __forceinline__ unsigned xb_ld(unsigned* p)              { return __hip_atomic_load(p, __ATOMIC_RELAXED, __HIP_MEMORY_SCOPE_AGENT); }
; __device__ __forceinline__ unsigned xb_add(unsigned* p, unsigned v) { return __hip_atomic_fetch_add(p, v, __ATOMIC_RELAXED, __HIP_MEMORY_SCOPE_AGENT); }
; #define XB_SPIN(cond, bar) do { unsigned _sp = 0; while (cond) { __builtin_amdgcn_s_sleep(1); \
;     if ((++_sp & 255u) == 0u) { if (xb_ld(&(bar)[XB_TMO])) break; if (_sp > XB_SPIN_CAP) { atomicAdd(&(bar)[XB_TMO], 1u); break; } } } } while (0)
; __device__ __forceinline__ void xcd_barrier(const XcdBarrier& b) {
;     ...
;         const unsigned old = xb_add(&bar[XB_XSUB(b.x)], 1u);
;         const unsigned gen = old / nloc;
;         if (old + 1u == (gen + 1u) * nloc) {
;             __builtin_amdgcn_fence(__ATOMIC_RELEASE, "agent");
;             asm volatile("s_waitcnt vmcnt(0)" ::: "memory");
;             const unsigned og = xb_add(&bar[XB_TOP], 1u);
;             const unsigned tg = og / nx;
;             if (og + 1u == (tg + 1u) * nx) xb_add(&bar[XB_TOPGEN], 1u);
;             else XB_SPIN(xb_ld(&bar[XB_TOPGEN]) == tg, bar);
;             __builtin_amdgcn_fence(__ATOMIC_ACQUIRE, "agent");
;             xb_add(&bar[XB_XGEN(b.x)], 1u);
;             asm volatile("s_waitcnt vmcnt(0)" ::: "memory");
;         } else {
;             XB_SPIN(xb_ld(&bar[XB_XGEN(b.x)]) == gen, bar);
.LBB0_242:
	s_or_b64 exec, exec, s[12:13]
	v_cvt_f32_u32_e32 v4, v2
	s_waitcnt vmcnt(0)
	v_readfirstlane_b32 s0, v3
	v_sub_u32_e32 v3, 0, v2
	v_rcp_iflag_f32_e32 v4, v4
	v_add_u32_e32 v5, s0, v1
	v_mul_f32_e32 v4, 0x4f7ffffe, v4
	v_cvt_u32_f32_e32 v4, v4
	v_mul_lo_u32 v1, v3, v4
	v_mul_hi_u32 v1, v4, v1
	v_add_u32_e32 v1, v4, v1
	v_mul_hi_u32 v1, v5, v1
	v_mul_lo_u32 v3, v1, v2
	v_sub_u32_e32 v3, v5, v3
	v_add_u32_e32 v4, 1, v1
	v_cmp_ge_u32_e32 vcc, v3, v2
	s_nop 1
	v_cndmask_b32_e32 v1, v1, v4, vcc
	v_sub_u32_e32 v4, v3, v2
	v_cndmask_b32_e32 v3, v3, v4, vcc
	v_add_u32_e32 v4, 1, v1
	v_cmp_ge_u32_e32 vcc, v3, v2
	v_add_u32_e32 v3, 1, v5
	s_nop 0
	v_cndmask_b32_e32 v1, v1, v4, vcc
	v_mul_lo_u32 v4, v2, v1
	v_add_u32_e32 v2, v4, v2
	v_cmp_ne_u32_e32 vcc, v3, v2
	s_and_saveexec_b64 s[12:13], vcc
	s_xor_b64 s[12:13], exec, s[12:13]
	s_cbranch_execz .LBB0_256
	v_readlane_b32 s24, v253, 2
	v_readlane_b32 s25, v253, 3
	s_waitcnt lgkmcnt(0)
	s_nop 3
	global_load_dword v0, v185, s[24:25] sc1
	s_waitcnt vmcnt(0)
	v_cmp_eq_u32_e32 vcc, v0, v1
	s_and_saveexec_b64 s[24:25], vcc
	s_cbranch_execz .LBB0_255
	s_mov_b32 s0, 1
	s_mov_b64 s[26:27], 0
	s_branch .LBB0_246

; __device__ __forceinline__ unsigned xb_ld(unsigned* p)              { return __hip_atomic_load(p, __ATOMIC_RELAXED, __HIP_MEMORY_SCOPE_AGENT); }
; #define XB_SPIN(cond, bar) do { unsigned _sp = 0; while (cond) { __builtin_amdgcn_s_sleep(1); \
;     if ((++_sp & 255u) == 0u) { if (xb_ld(&(bar)[XB_TMO])) break; if (_sp > XB_SPIN_CAP) { atomicAdd(&(bar)[XB_TMO], 1u); break; } } } } while (0)
; __device__ __forceinline__ void xcd_barrier(const XcdBarrier& b) {
;     ...
;             XB_SPIN(xb_ld(&bar[XB_XGEN(b.x)]) == gen, bar);
.LBB0_250:
	v_readlane_b32 s36, v253, 2
	v_readlane_b32 s37, v253, 3
	s_add_i32 s0, s0, 1
	s_mov_b64 s[38:39], -1
	s_nop 2
	global_load_dword v0, v185, s[36:37] sc1
	s_waitcnt vmcnt(0)
	v_cmp_ne_u32_e32 vcc, v0, v1
	s_orn2_b64 s[36:37], vcc, exec
	s_branch .LBB0_245

; __device__ __forceinline__ unsigned xb_ld(unsigned* p)              { return __hip_atomic_load(p, __ATOMIC_RELAXED, __HIP_MEMORY_SCOPE_AGENT); }
; #define XB_SPIN(cond, bar) do { unsigned _sp = 0; while (cond) { __builtin_amdgcn_s_sleep(1); \
;     if ((++_sp & 255u) == 0u) { if (xb_ld(&(bar)[XB_TMO])) break; if (_sp > XB_SPIN_CAP) { atomicAdd(&(bar)[XB_TMO], 1u); break; } } } } while (0)
; __device__ __forceinline__ void xcd_barrier(const XcdBarrier& b) {
;     ...
;             XB_SPIN(xb_ld(&bar[XB_XGEN(b.x)]) == gen, bar);
.LBB0_1471:
	v_readlane_b32 s38, v253, 2
	v_readlane_b32 s39, v253, 3
	s_add_i32 s0, s0, 1
	s_mov_b64 s[40:41], -1
	s_nop 2
	global_load_dword v0, v185, s[38:39] sc1
	s_waitcnt vmcnt(0)
	v_cmp_ne_u32_e32 vcc, v0, v1
	s_orn2_b64 s[38:39], vcc, exec
	s_branch .LBB0_1466
